# v55 plus foxprep logit/bias loads hoisted (1 round trip per step), FoX row max via v_permlane32_swap instead of ds_bpermute, skip o*=alpha when alpha==1 in every lane
# baseline (speedup 1.0000x reference)
.LBB0_115:
	s_cmpk_gt_i32 s4, 0x3ff
	s_mov_b64 s[2:3], -1
	s_cbranch_scc0 .LBB0_121
	s_mov_b32 s2, 10
	s_bfe_u32 s37, s4, 0x20008
	s_ashr_i32 s3, s2, 31
	s_bfe_u32 s50, s6, 0x80005
	s_lshl_b32 s51, s37, 22
	s_lshl_b64 s[2:3], s[2:3], 3
	s_add_u32 s2, s0, s2
	s_addc_u32 s3, s1, s3
	s_load_dwordx2 s[2:3], s[2:3], 0x0
	v_mov_b32_e32 v3, v183
	s_mov_b32 s21, s81
	v_and_b32_e32 v4, 63, v3
	s_waitcnt lgkmcnt(0)
	s_add_u32 s2, s2, s44
	v_lshlrev_b32_e32 v12, 16, v3
	v_bfe_u32 v5, v3, 2, 4
	v_and_b32_e32 v2, 3, v3
	v_and_b32_e32 v3, 60, v3
	s_addc_u32 s3, s3, s45
	v_lshlrev_b32_e32 v0, 2, v2
	v_lshl_or_b32 v3, s37, 17, v3
	v_cmp_gt_u32_e64 s[38:39], 32, v4
	v_lshl_add_u64 v[6:7], s[2:3], 0, v[0:1]
	v_lshlrev_b32_e32 v0, 3, v4
	v_add_u32_e32 v4, s7, v5
	v_lshl_or_b32 v3, v2, 15, v3
	v_and_b32_e32 v13, 0xf0000, v12
	v_mul_lo_u32 v25, v4, s18
	v_lshl_or_b32 v4, s50, 7, v3
	v_and_b32_e32 v3, 0x300000, v12
	s_mov_b32 s31, s81
	s_mov_b32 s35, s81
	s_mov_b32 s41, s81
	s_mov_b32 s43, s81
	v_lshl_add_u64 v[8:9], s[26:27], 0, v[0:1]
	v_mov_b32_e32 v5, v1
	s_mov_b64 s[2:3], 0x1d710000
	v_or3_b32 v3, s51, v3, v13
	v_or_b32_e32 v0, 0x9600c00, v0
	v_lshl_add_u64 v[10:11], v[4:5], 0, s[2:3]
	v_lshl_or_b32 v12, s50, 6, v3
	v_mov_b32_e32 v13, v1
	s_mov_b32 s2, 0
	v_lshl_add_u64 v[14:15], s[20:21], 1, v[0:1]
	v_lshl_add_u64 v[16:17], s[30:31], 1, v[0:1]
	v_lshl_add_u64 v[18:19], s[34:35], 1, v[0:1]
	v_lshl_add_u64 v[20:21], s[40:41], 1, v[0:1]
	v_lshl_add_u64 v[22:23], s[42:43], 1, v[0:1]
	v_lshlrev_b32_e32 v24, 1, v2
	v_mov_b32_e32 v0, v25
	global_load_dword v55, v[6:7], off
	s_branch .LBB0_118

.LBB0_118:
	v_lshl_add_u64 v[2:3], s[72:73], 0, v[22:23]
	v_lshl_add_u64 v[4:5], s[72:73], 0, v[20:21]
	v_lshl_add_u64 v[26:27], s[72:73], 0, v[18:19]
	flat_load_dwordx2 v[2:3], v[2:3]
	s_add_i32 s3, s11, s2
	flat_load_dwordx2 v[4:5], v[4:5]
	s_add_i32 s80, s3, 0xf8804b00
	flat_load_dwordx2 v[38:39], v[26:27]
	v_lshl_add_u64 v[26:27], s[72:73], 0, v[16:17]
	flat_load_dwordx2 v[40:41], v[26:27]
	v_lshl_add_u64 v[26:27], s[72:73], 0, v[14:15]
	flat_load_dwordx2 v[42:43], v[26:27]
	v_lshl_add_u64 v[26:27], s[80:81], 1, v[8:9]
	s_add_i32 s80, s3, 0xf8805a00
	flat_load_dwordx2 v[44:45], v[26:27] offset:3072
	v_lshl_add_u64 v[26:27], s[80:81], 1, v[8:9]
	s_add_i32 s80, s3, 0xf8806900
	flat_load_dwordx2 v[46:47], v[26:27] offset:3072
	v_lshl_add_u64 v[26:27], s[80:81], 1, v[8:9]
	flat_load_dwordx2 v[48:49], v[26:27] offset:3072
	v_lshl_add_u64 v[50:51], s[72:73], 0, v[12:13]
	s_mov_b32 s3, 0x18600000
	s_and_saveexec_b64 s[50:51], s[38:39]
	v_lshl_add_u64 v[56:57], s[26:27], 0, v[0:1]
	v_add_co_u32_e32 v56, vcc, v56, v24
	s_nop 1
	v_addc_co_u32_e32 v57, vcc, 0, v57, vcc
	v_add_co_u32_e32 v56, vcc, 0x1000, v56
	s_nop 1
	v_addc_co_u32_e32 v57, vcc, 0, v57, vcc
	flat_load_ushort v58, v[56:57] offset:3104
	s_or_b64 exec, exec, s[50:51]
	s_waitcnt vmcnt(0) lgkmcnt(0)
	v_and_b32_e32 v25, 0xffff, v2
	v_lshrrev_b32_e32 v2, 16, v2
	v_and_or_b32 v30, v4, s33, v2
	v_lshl_or_b32 v26, v4, 16, v25
	v_lshrrev_b32_e32 v2, 16, v38
	v_and_b32_e32 v25, 0xffff, v38
	v_and_or_b32 v31, v40, s33, v2
	v_lshl_or_b32 v27, v40, 16, v25
	v_lshrrev_b32_e32 v2, 16, v42
	v_and_b32_e32 v25, 0xffff, v42
	v_add_co_u32_e32 v38, vcc, s3, v50
	v_and_or_b32 v32, v44, s33, v2
	v_lshl_or_b32 v28, v44, 16, v25
	v_lshrrev_b32_e32 v2, 16, v46
	v_and_b32_e32 v25, 0xffff, v46
	v_and_or_b32 v33, v48, s33, v2
	v_and_b32_e32 v2, 0xffff, v3
	v_lshl_or_b32 v34, v5, 16, v2
	v_and_b32_e32 v2, 0xffff, v39
	v_lshl_or_b32 v35, v41, 16, v2
	v_and_b32_e32 v2, 0xffff, v43
	v_lshl_or_b32 v36, v45, 16, v2
	v_and_b32_e32 v2, 0xffff, v47
	v_lshl_or_b32 v29, v48, 16, v25
	v_lshl_or_b32 v37, v49, 16, v2
	v_lshrrev_b32_e32 v2, 16, v3
	v_lshrrev_b32_e32 v3, 16, v39
	v_addc_co_u32_e32 v39, vcc, 0, v51, vcc
	s_mov_b32 s3, 0x18604000
	flat_store_dwordx4 v[38:39], v[26:29]
	v_and_or_b32 v2, v5, s33, v2
	v_lshrrev_b32_e32 v4, 16, v43
	v_add_co_u32_e32 v26, vcc, s3, v50
	v_lshrrev_b32_e32 v5, 16, v47
	s_nop 0
	v_addc_co_u32_e32 v27, vcc, 0, v51, vcc
	flat_store_dwordx4 v[26:27], v[30:33]
	v_add_co_u32_e32 v26, vcc, 0x18608000, v50
	v_and_or_b32 v3, v41, s33, v3
	s_nop 0
	v_addc_co_u32_e32 v27, vcc, 0, v51, vcc
	flat_store_dwordx4 v[26:27], v[34:37]
	v_add_co_u32_e32 v26, vcc, 0x1860c000, v50
	v_and_or_b32 v4, v45, s33, v4
	v_and_or_b32 v5, v49, s33, v5
	v_addc_co_u32_e32 v27, vcc, 0, v51, vcc
	flat_store_dwordx4 v[26:27], v[2:5]
	s_and_saveexec_b64 s[50:51], s[38:39]
	s_cbranch_execz .LBB0_117
	v_lshlrev_b32_e32 v2, 16, v58
	v_add_f32_e32 v3, v55, v2
	v_min_f32_e32 v2, 0, v3
	v_mul_f32_e64 v3, |v3|, s19
	v_exp_f32_e32 v3, v3
	s_nop 0
	v_add_f32_e32 v25, 1.0, v3
	v_add_f32_e32 v4, -1.0, v25
	v_sub_f32_e32 v5, v4, v25
	v_add_f32_e32 v5, 1.0, v5
	v_sub_f32_e32 v4, v3, v4
	v_add_f32_e32 v26, v4, v5
	v_frexp_mant_f32_e32 v4, v25
	v_cmp_gt_f32_e32 vcc, s86, v4
	v_cvt_f64_f32_e32 v[4:5], v25
	v_frexp_exp_i32_f64_e32 v4, v[4:5]
	v_subbrev_co_u32_e32 v32, vcc, 0, v4, vcc
	v_sub_u32_e32 v4, 0, v32
	v_ldexp_f32 v5, v25, v4
	v_add_f32_e32 v25, -1.0, v5
	v_add_f32_e32 v27, 1.0, v5
	v_ldexp_f32 v4, v26, v4
	v_add_f32_e32 v26, 1.0, v25
	v_add_f32_e32 v28, -1.0, v27
	v_sub_f32_e32 v26, v5, v26
	v_sub_f32_e32 v5, v5, v28
	v_add_f32_e32 v26, v4, v26
	v_add_f32_e32 v4, v4, v5
	v_add_f32_e32 v33, v27, v4
	v_rcp_f32_e32 v35, v33
	v_sub_f32_e32 v5, v33, v27
	v_sub_f32_e32 v34, v4, v5
	v_add_f32_e32 v5, v25, v26
	v_sub_f32_e32 v4, v5, v25
	v_mul_f32_e32 v36, v5, v35
	v_sub_f32_e32 v25, v26, v4
	v_mul_f32_e32 v26, v33, v36
	v_fma_f32 v28, v36, v33, -v26
	v_fmac_f32_e32 v28, v36, v34
	v_add_f32_e32 v4, v26, v28
	v_sub_f32_e32 v27, v5, v4
	v_pk_add_f32 v[30:31], v[4:5], v[26:27] neg_lo:[0,1] neg_hi:[0,1]
	v_mov_b32_e32 v29, v4
	v_pk_add_f32 v[4:5], v[30:31], v[28:29] neg_lo:[0,1] neg_hi:[0,1]
	v_cmp_neq_f32_e32 vcc, s15, v3
	v_add_f32_e32 v5, v25, v5
	v_add_f32_e32 v4, v4, v5
	v_add_f32_e32 v5, v27, v4
	v_mul_f32_e32 v25, v35, v5
	v_mul_f32_e32 v26, v33, v25
	v_fma_f32 v28, v25, v33, -v26
	v_fmac_f32_e32 v28, v25, v34
	v_sub_f32_e32 v27, v27, v5
	v_add_f32_e32 v33, v4, v27
	v_add_f32_e32 v4, v26, v28
	v_sub_f32_e32 v27, v5, v4
	v_pk_add_f32 v[30:31], v[4:5], v[26:27] neg_lo:[0,1] neg_hi:[0,1]
	v_mov_b32_e32 v29, v4
	v_pk_add_f32 v[4:5], v[30:31], v[28:29] neg_lo:[0,1] neg_hi:[0,1]
	s_nop 0
	v_add_f32_e32 v5, v33, v5
	v_add_f32_e32 v4, v4, v5
	v_add_f32_e32 v5, v36, v25
	v_add_f32_e32 v4, v27, v4
	v_sub_f32_e32 v26, v5, v36
	v_mul_f32_e32 v4, v35, v4
	v_sub_f32_e32 v25, v25, v26
	v_add_f32_e32 v25, v25, v4
	v_add_f32_e32 v26, v5, v25
	v_mul_f32_e32 v28, v26, v26
	v_fmamk_f32 v4, v28, 0x3e9b6dac, v172
	v_fmaak_f32 v147, v28, v4, 0x3f2aaada
	v_cvt_f32_i32_e32 v4, v32
	v_sub_f32_e32 v5, v26, v5
	v_sub_f32_e32 v5, v25, v5
	v_ldexp_f32 v25, v5, 1
	v_mul_f32_e32 v5, v26, v28
	v_pk_mul_f32 v[28:29], v[4:5], v[146:147]
	v_ldexp_f32 v27, v26, 1
	v_fma_f32 v26, v4, s87, -v28
	v_fmac_f32_e32 v26, 0xb102e308, v4
	v_pk_add_f32 v[4:5], v[28:29], v[26:27]
	v_mov_b32_e32 v30, v28
	v_sub_f32_e32 v27, v5, v27
	v_sub_f32_e32 v27, v29, v27
	v_add_f32_e32 v31, v25, v27
	v_pk_add_f32 v[28:29], v[4:5], v[28:29] neg_lo:[0,1] neg_hi:[0,1]
	v_pk_add_f32 v[32:33], v[4:5], v[30:31]
	v_mov_b32_e32 v27, v4
	v_mov_b32_e32 v29, v33
	v_pk_add_f32 v[34:35], v[26:27], v[28:29] neg_lo:[0,1] neg_hi:[0,1]
	v_pk_add_f32 v[26:27], v[26:27], v[28:29]
	v_mov_b32_e32 v30, v31
	v_pk_add_f32 v[28:29], v[26:27], v[4:5] op_sel:[1,0] op_sel_hi:[0,1] neg_lo:[0,1] neg_hi:[0,1]
	v_pk_add_f32 v[36:37], v[32:33], v[28:29] op_sel_hi:[1,0] neg_lo:[0,1] neg_hi:[0,1]
	v_mov_b32_e32 v32, v33
	v_mov_b32_e32 v33, v27
	v_pk_mov_b32 v[28:29], v[4:5], v[28:29] op_sel:[1,0]
	v_mov_b32_e32 v31, v4
	v_pk_add_f32 v[28:29], v[32:33], v[28:29] neg_lo:[0,1] neg_hi:[0,1]
	v_mov_b32_e32 v36, v34
	v_pk_add_f32 v[4:5], v[30:31], v[28:29] neg_lo:[0,1] neg_hi:[0,1]
	v_mov_b32_e32 v35, v27
	v_pk_add_f32 v[28:29], v[36:37], v[4:5]
	s_nop 0
	v_pk_add_f32 v[30:31], v[28:29], v[28:29] op_sel:[0,1] op_sel_hi:[1,0]
	s_nop 0
	v_pk_add_f32 v[26:27], v[26:27], v[30:31] op_sel:[1,0] op_sel_hi:[0,1]
	v_mov_b32_e32 v29, v26
	v_pk_add_f32 v[32:33], v[28:29], v[34:35] neg_lo:[0,1] neg_hi:[0,1]
	v_mov_b32_e32 v5, v30
	v_sub_f32_e32 v25, v28, v32
	v_pk_add_f32 v[4:5], v[4:5], v[32:33] neg_lo:[0,1] neg_hi:[0,1]
	v_sub_f32_e32 v25, v34, v25
	v_add_f32_e32 v4, v4, v25
	v_add_f32_e32 v4, v4, v5
	v_add_f32_e32 v4, v26, v4
	v_cndmask_b32_e32 v4, v175, v4, vcc
	v_cmp_ngt_f32_e32 vcc, -1.0, v3
	s_nop 1
	v_cndmask_b32_e32 v4, v176, v4, vcc
	v_cmp_neq_f32_e32 vcc, -1.0, v3
	s_nop 1
	v_cndmask_b32_e32 v4, v177, v4, vcc
	v_cmp_lt_f32_e64 vcc, |v3|, s88
	s_nop 1
	v_cndmask_b32_e32 v3, v4, v3, vcc
	v_sub_f32_e32 v4, v2, v3
	v_lshl_add_u64 v[2:3], s[72:73], 0, v[10:11]
	flat_store_dword v[2:3], v4
	s_branch .LBB0_117

.LBB0_326:
	s_or_b64 exec, exec, s[2:3]
	s_mov_b64 s[2:3], 0
	v_max3_f32 v0, v64, v65, v66
	v_max3_f32 v14, v80, v81, v82
	v_max3_f32 v0, v0, v67, v68
	v_max3_f32 v14, v14, v83, v84
	v_max3_f32 v0, v0, v69, v70
	v_max3_f32 v14, v14, v85, v86
	v_max3_f32 v0, v0, v71, v72
	v_max3_f32 v14, v14, v87, v88
	v_max3_f32 v0, v0, v73, v74
	v_max3_f32 v14, v14, v89, v90
	v_max3_f32 v0, v0, v75, v76
	v_max3_f32 v14, v14, v91, v92
	v_max3_f32 v0, v0, v77, v78
	v_max3_f32 v14, v14, v93, v94
	v_max3_f32 v0, v0, v79, v95
	v_max_f32_e32 v0, v0, v14
	v_mov_b32_e32 v14, v0
	s_nop 1
	v_permlane32_swap_b32_e32 v14, v0
	ds_read2_b64 v[2:5], v252 offset1:2
	ds_read2_b64 v[6:9], v253 offset0:64 offset1:66
	ds_read2_b64 v[10:13], v252 offset0:8 offset1:10
	ds_read2_b64 v[224:227], v253 offset0:72 offset1:74
	ds_read2_b64 v[228:231], v252 offset0:4 offset1:6
	ds_read2_b64 v[232:235], v253 offset0:68 offset1:70
	ds_read2_b64 v[236:239], v252 offset0:12 offset1:14
	ds_read2_b64 v[240:243], v253 offset0:76 offset1:78
	v_max3_f32 v144, v161, v0, v14
	v_sub_f32_e32 v0, v161, v144
	v_mov_b32_e32 v161, v144
	v_exp_f32_e32 v0, v0
	v_pk_add_f32 v[64:65], v[64:65], v[144:145] op_sel_hi:[1,0] neg_lo:[0,1] neg_hi:[0,1]
	v_pk_add_f32 v[66:67], v[66:67], v[144:145] op_sel_hi:[1,0] neg_lo:[0,1] neg_hi:[0,1]
	v_pk_add_f32 v[68:69], v[68:69], v[144:145] op_sel_hi:[1,0] neg_lo:[0,1] neg_hi:[0,1]
	v_pk_add_f32 v[70:71], v[70:71], v[144:145] op_sel_hi:[1,0] neg_lo:[0,1] neg_hi:[0,1]
	v_pk_add_f32 v[72:73], v[72:73], v[144:145] op_sel_hi:[1,0] neg_lo:[0,1] neg_hi:[0,1]
	v_pk_add_f32 v[74:75], v[74:75], v[144:145] op_sel_hi:[1,0] neg_lo:[0,1] neg_hi:[0,1]
	v_pk_add_f32 v[76:77], v[76:77], v[144:145] op_sel_hi:[1,0] neg_lo:[0,1] neg_hi:[0,1]
	v_pk_add_f32 v[78:79], v[78:79], v[144:145] op_sel_hi:[1,0] neg_lo:[0,1] neg_hi:[0,1]
	v_pk_add_f32 v[80:81], v[80:81], v[144:145] op_sel_hi:[1,0] neg_lo:[0,1] neg_hi:[0,1]
	v_pk_add_f32 v[82:83], v[82:83], v[144:145] op_sel_hi:[1,0] neg_lo:[0,1] neg_hi:[0,1]
	v_pk_add_f32 v[84:85], v[84:85], v[144:145] op_sel_hi:[1,0] neg_lo:[0,1] neg_hi:[0,1]
	v_pk_add_f32 v[86:87], v[86:87], v[144:145] op_sel_hi:[1,0] neg_lo:[0,1] neg_hi:[0,1]
	v_pk_add_f32 v[88:89], v[88:89], v[144:145] op_sel_hi:[1,0] neg_lo:[0,1] neg_hi:[0,1]
	v_pk_add_f32 v[90:91], v[90:91], v[144:145] op_sel_hi:[1,0] neg_lo:[0,1] neg_hi:[0,1]
	v_pk_add_f32 v[92:93], v[92:93], v[144:145] op_sel_hi:[1,0] neg_lo:[0,1] neg_hi:[0,1]
	v_pk_add_f32 v[94:95], v[94:95], v[144:145] op_sel_hi:[1,0] neg_lo:[0,1] neg_hi:[0,1]
	v_exp_f32_e32 v64, v64
	v_exp_f32_e32 v65, v65
	v_exp_f32_e32 v66, v66
	v_exp_f32_e32 v67, v67
	v_exp_f32_e32 v68, v68
	v_exp_f32_e32 v69, v69
	v_exp_f32_e32 v70, v70
	v_exp_f32_e32 v71, v71
	v_exp_f32_e32 v80, v80
	v_exp_f32_e32 v81, v81
	v_exp_f32_e32 v82, v82
	v_exp_f32_e32 v83, v83
	v_exp_f32_e32 v84, v84
	v_exp_f32_e32 v85, v85
	v_exp_f32_e32 v86, v86
	v_exp_f32_e32 v87, v87
	v_cmp_neq_f32_e32 vcc, 1.0, v0
	s_and_b64 vcc, exec, vcc
	v_exp_f32_e32 v72, v72
	v_exp_f32_e32 v73, v73
	v_exp_f32_e32 v74, v74
	v_exp_f32_e32 v75, v75
	v_exp_f32_e32 v76, v76
	v_exp_f32_e32 v77, v77
	v_exp_f32_e32 v78, v78
	v_exp_f32_e32 v79, v79
	v_exp_f32_e32 v88, v88
	v_exp_f32_e32 v89, v89
	v_exp_f32_e32 v90, v90
	v_exp_f32_e32 v91, v91
	v_exp_f32_e32 v92, v92
	v_exp_f32_e32 v93, v93
	v_exp_f32_e32 v94, v94
	v_exp_f32_e32 v95, v95
	s_cbranch_vccz .Lfox_noscale
	v_pk_mul_f32 v[34:35], v[34:35], v[0:1] op_sel_hi:[1,0]
	v_pk_mul_f32 v[36:37], v[36:37], v[0:1] op_sel_hi:[1,0]
	v_pk_mul_f32 v[38:39], v[38:39], v[0:1] op_sel_hi:[1,0]
	v_pk_mul_f32 v[40:41], v[40:41], v[0:1] op_sel_hi:[1,0]
	v_pk_mul_f32 v[42:43], v[42:43], v[0:1] op_sel_hi:[1,0]
	v_pk_mul_f32 v[44:45], v[44:45], v[0:1] op_sel_hi:[1,0]
	v_pk_mul_f32 v[46:47], v[46:47], v[0:1] op_sel_hi:[1,0]
	v_pk_mul_f32 v[48:49], v[48:49], v[0:1] op_sel_hi:[1,0]
	v_pk_mul_f32 v[18:19], v[18:19], v[0:1] op_sel_hi:[1,0]
	v_pk_mul_f32 v[20:21], v[20:21], v[0:1] op_sel_hi:[1,0]
	v_pk_mul_f32 v[22:23], v[22:23], v[0:1] op_sel_hi:[1,0]
	v_pk_mul_f32 v[24:25], v[24:25], v[0:1] op_sel_hi:[1,0]
	v_pk_mul_f32 v[26:27], v[26:27], v[0:1] op_sel_hi:[1,0]
	v_pk_mul_f32 v[28:29], v[28:29], v[0:1] op_sel_hi:[1,0]
	v_pk_mul_f32 v[30:31], v[30:31], v[0:1] op_sel_hi:[1,0]
	v_pk_mul_f32 v[32:33], v[32:33], v[0:1] op_sel_hi:[1,0]
.Lfox_noscale:
	v_pk_add_f32 v[214:215], v[64:65], v[80:81]
	v_pk_add_f32 v[216:217], v[66:67], v[82:83]
	v_pk_add_f32 v[244:245], v[68:69], v[84:85]
	v_pk_add_f32 v[246:247], v[70:71], v[86:87]
	v_cvt_pk_bf16_f32 v64, v64, v65
	v_cvt_pk_bf16_f32 v65, v66, v67
	v_cvt_pk_bf16_f32 v66, v68, v69
	v_cvt_pk_bf16_f32 v67, v70, v71
	v_cvt_pk_bf16_f32 v80, v80, v81
	v_cvt_pk_bf16_f32 v81, v82, v83
	v_cvt_pk_bf16_f32 v82, v84, v85
	v_cvt_pk_bf16_f32 v83, v86, v87
	v_pk_add_f32 v[248:249], v[72:73], v[88:89]
	v_pk_add_f32 v[250:251], v[74:75], v[90:91]
	v_pk_add_f32 v[14:15], v[76:77], v[92:93]
	v_pk_add_f32 v[218:219], v[78:79], v[94:95]
	s_waitcnt lgkmcnt(4)
	v_mfma_f32_32x32x16_bf16 v[34:49], v[2:5], v[64:67], v[34:49]
	v_mfma_f32_32x32x16_bf16 v[18:33], v[6:9], v[64:67], v[18:33]
	v_mfma_f32_32x32x16_bf16 v[34:49], v[10:13], v[80:83], v[34:49]
	v_mfma_f32_32x32x16_bf16 v[18:33], v[224:227], v[80:83], v[18:33]
	v_cvt_pk_bf16_f32 v68, v72, v73
	v_cvt_pk_bf16_f32 v69, v74, v75
	v_cvt_pk_bf16_f32 v70, v76, v77
	v_cvt_pk_bf16_f32 v71, v78, v79
	v_cvt_pk_bf16_f32 v84, v88, v89
	v_cvt_pk_bf16_f32 v85, v90, v91
	v_cvt_pk_bf16_f32 v86, v92, v93
	v_cvt_pk_bf16_f32 v87, v94, v95
	v_add_f32_e32 v144, 0, v214
	v_add_f32_e32 v144, v215, v144
	v_add_f32_e32 v144, v216, v144
	v_add_f32_e32 v144, v217, v144
	v_add_f32_e32 v144, v244, v144
	v_add_f32_e32 v144, v245, v144
	v_add_f32_e32 v144, v246, v144
	v_add_f32_e32 v144, v247, v144
	s_waitcnt lgkmcnt(0)
	v_mfma_f32_32x32x16_bf16 v[34:49], v[228:231], v[68:71], v[34:49]
	v_mfma_f32_32x32x16_bf16 v[18:33], v[232:235], v[68:71], v[18:33]
	v_mfma_f32_32x32x16_bf16 v[34:49], v[236:239], v[84:87], v[34:49]
	v_mfma_f32_32x32x16_bf16 v[18:33], v[240:243], v[84:87], v[18:33]
	v_add_f32_e32 v144, v248, v144
	v_add_f32_e32 v144, v249, v144
	v_add_f32_e32 v144, v250, v144
	v_add_f32_e32 v144, v251, v144
	v_add_f32_e32 v144, v14, v144
	v_add_f32_e32 v144, v15, v144
	v_add_f32_e32 v144, v218, v144
	v_add_f32_e32 v144, v219, v144
	v_fma_f32 v202, v202, v0, v144
